# G1 epilogue: v_cvt_pk_bf16_f32 packs + v_permlane16_swap row exchange, 16 global_store_dwordx4 per wave instead of 32 dwordx2 (store-issue-bound tail halved)
# speedup vs baseline: 1.1825x; 1.0224x over previous
; __device__ __forceinline__ void gemm_core_big(const bf16_t* __restrict__ A, int lda, const bf16_t* __restrict__ Bt, int ldb,
;                                               int K, f32x4 (&acc)[8][4], char* smem) {
;     ...
;   for (int kt = 0; kt < nk; ++kt) {
;     __syncthreads();
; #pragma unroll
;     for (int i = 0; i < 8; ++i) *(u32x4*)(wA + 32 * i * LDS_STRIDE) = ra[i];
; #pragma unroll
;     for (int i = 0; i < 4; ++i) *(u32x4*)(wB + 32 * i * LDS_STRIDE) = rb[i];
;     __syncthreads();
;     {
;       const int k1 = min(kt + 1, nk - 1) << 6;
; #pragma unroll
;       for (int i = 0; i < 8; ++i) ra[i] = *(const u32x4*)(ap + (size_t)(32 * i) * lda + k1);
; #pragma unroll
;       for (int i = 0; i < 4; ++i) rb[i] = *(const u32x4*)(bp + (size_t)(32 * i) * ldb + k1);
;     }
; #pragma unroll
;     for (int ks = 0; ks < 2; ++ks) {
;       const int fo = ks ? fo1 : fo0;
;       bf16x8 bfr[4];
; #pragma unroll
;       for (int j = 0; j < 4; ++j) bfr[j] = *(const bf16x8*)(cB + j * 16 * LDS_STRIDE + fo);
; #pragma unroll
;       for (int i = 0; i < 8; ++i) {
;         const bf16x8 af = *(const bf16x8*)(cA + i * 16 * LDS_STRIDE + fo);
; #pragma unroll
;         for (int j = 0; j < 4; ++j)
;           acc[i][j] = __builtin_amdgcn_mfma_f32_16x16x32_bf16(bfr[j], af, acc[i][j], 0, 0, 0);
;       }
;     }
.LBB0_711:
	s_setprio 0
	global_load_dwordx4 v[144:147], v224, s[30:31]
	global_load_dwordx4 v[148:151], v224, s[28:29]
	global_load_dwordx4 v[134:137], v225, s[28:29]
	global_load_dwordx4 v[152:155], v226, s[28:29]
	global_load_dwordx4 v[156:159], v227, s[28:29]
	global_load_dwordx4 v[160:163], v228, s[28:29]
	global_load_dwordx4 v[164:167], v229, s[28:29]
	global_load_dwordx4 v[168:171], v230, s[28:29]
	global_load_dwordx4 v[172:175], v231, s[28:29]
	global_load_dwordx4 v[188:191], v225, s[30:31]
	global_load_dwordx4 v[192:195], v226, s[30:31]
	global_load_dwordx4 v[196:199], v227, s[30:31]
	s_add_u32 s28, s28, 0x80
	s_addc_u32 s29, s29, 0
	s_add_u32 s30, s30, 0x80
	s_addc_u32 s31, s31, 0
	s_barrier
	s_add_i32 s26, s26, 1
	s_lshl_b32 s18, s13, 7
	s_cmp_lg_u32 s26, 17
	s_waitcnt vmcnt(10)
	ds_write_b128 v2, v[148:151]
	ds_write_b128 v2, v[144:147] offset:32768
	s_waitcnt vmcnt(9)
	ds_write_b128 v2, v[134:137] offset:4096
	s_waitcnt vmcnt(8)
	ds_write_b128 v2, v[152:155] offset:8192
	s_waitcnt vmcnt(7)
	ds_write_b128 v2, v[156:159] offset:12288
	s_waitcnt vmcnt(6)
	ds_write_b128 v2, v[160:163] offset:16384
	s_waitcnt vmcnt(5)
	ds_write_b128 v2, v[164:167] offset:20480
	s_waitcnt vmcnt(4)
	ds_write_b128 v2, v[168:171] offset:24576
	s_waitcnt vmcnt(3)
	ds_write_b128 v2, v[172:175] offset:28672
	s_waitcnt vmcnt(2)
	ds_write_b128 v2, v[188:191] offset:36864
	s_waitcnt vmcnt(1)
	ds_write_b128 v2, v[192:195] offset:40960
	s_waitcnt vmcnt(0)
	ds_write_b128 v2, v[196:199] offset:45056
	s_waitcnt lgkmcnt(0)
	s_barrier
	ds_read_b128 v[134:137], v140 offset:32768
	ds_read_b128 v[144:147], v140 offset:34816
	ds_read_b128 v[156:159], v140 offset:36864
	ds_read_b128 v[160:163], v140 offset:38912
	ds_read_b128 v[148:151], v141 offset:0
	ds_read_b128 v[152:155], v141 offset:2048
	ds_read_b128 v[216:219], v141 offset:4096
	ds_read_b128 v[220:223], v141 offset:6144
	s_setprio 1
	s_waitcnt lgkmcnt(3)
	v_mfma_f32_16x16x32_bf16 v[128:131], v[134:137], v[148:151], v[128:131]
	v_mfma_f32_16x16x32_bf16 v[124:127], v[144:147], v[148:151], v[124:127]
	v_mfma_f32_16x16x32_bf16 v[120:123], v[156:159], v[148:151], v[120:123]
	v_mfma_f32_16x16x32_bf16 v[116:119], v[160:163], v[148:151], v[116:119]
	s_waitcnt lgkmcnt(2)
	v_mfma_f32_16x16x32_bf16 v[112:115], v[134:137], v[152:155], v[112:115]
	v_mfma_f32_16x16x32_bf16 v[108:111], v[144:147], v[152:155], v[108:111]
	v_mfma_f32_16x16x32_bf16 v[104:107], v[156:159], v[152:155], v[104:107]
	v_mfma_f32_16x16x32_bf16 v[100:103], v[160:163], v[152:155], v[100:103]
	ds_read_b128 v[148:151], v141 offset:8192
	ds_read_b128 v[152:155], v141 offset:10240
	s_waitcnt lgkmcnt(3)
	v_mfma_f32_16x16x32_bf16 v[96:99], v[134:137], v[216:219], v[96:99]
	v_mfma_f32_16x16x32_bf16 v[92:95], v[144:147], v[216:219], v[92:95]
	v_mfma_f32_16x16x32_bf16 v[88:91], v[156:159], v[216:219], v[88:91]
	v_mfma_f32_16x16x32_bf16 v[84:87], v[160:163], v[216:219], v[84:87]
	s_waitcnt lgkmcnt(2)
	v_mfma_f32_16x16x32_bf16 v[80:83], v[134:137], v[220:223], v[80:83]
	v_mfma_f32_16x16x32_bf16 v[76:79], v[144:147], v[220:223], v[76:79]
	v_mfma_f32_16x16x32_bf16 v[72:75], v[156:159], v[220:223], v[72:75]
	v_mfma_f32_16x16x32_bf16 v[68:71], v[160:163], v[220:223], v[68:71]
	ds_read_b128 v[216:219], v141 offset:12288
	ds_read_b128 v[220:223], v141 offset:14336
	ds_read_b128 v[200:203], v142 offset:32768
	ds_read_b128 v[204:207], v142 offset:34816
	ds_read_b128 v[208:211], v142 offset:36864
	ds_read_b128 v[212:215], v142 offset:38912
	s_waitcnt lgkmcnt(7)
	v_mfma_f32_16x16x32_bf16 v[64:67], v[134:137], v[148:151], v[64:67]
	v_mfma_f32_16x16x32_bf16 v[60:63], v[144:147], v[148:151], v[60:63]
	v_mfma_f32_16x16x32_bf16 v[56:59], v[156:159], v[148:151], v[56:59]
	v_mfma_f32_16x16x32_bf16 v[52:55], v[160:163], v[148:151], v[52:55]
	s_waitcnt lgkmcnt(6)
	v_mfma_f32_16x16x32_bf16 v[48:51], v[134:137], v[152:155], v[48:51]
	v_mfma_f32_16x16x32_bf16 v[44:47], v[144:147], v[152:155], v[44:47]
	v_mfma_f32_16x16x32_bf16 v[40:43], v[156:159], v[152:155], v[40:43]
	v_mfma_f32_16x16x32_bf16 v[36:39], v[160:163], v[152:155], v[36:39]
	ds_read_b128 v[148:151], v143 offset:0
	ds_read_b128 v[152:155], v143 offset:2048
	s_waitcnt lgkmcnt(7)
	v_mfma_f32_16x16x32_bf16 v[32:35], v[134:137], v[216:219], v[32:35]
	v_mfma_f32_16x16x32_bf16 v[24:27], v[144:147], v[216:219], v[24:27]
	v_mfma_f32_16x16x32_bf16 v[20:23], v[156:159], v[216:219], v[20:23]
	v_mfma_f32_16x16x32_bf16 v[16:19], v[160:163], v[216:219], v[16:19]
	s_waitcnt lgkmcnt(6)
	v_mfma_f32_16x16x32_bf16 v[12:15], v[134:137], v[220:223], v[12:15]
	v_mfma_f32_16x16x32_bf16 v[8:11], v[144:147], v[220:223], v[8:11]
	v_mfma_f32_16x16x32_bf16 v[4:7], v[156:159], v[220:223], v[4:7]
	v_mfma_f32_16x16x32_bf16 v[28:31], v[160:163], v[220:223], v[28:31]
	ds_read_b128 v[216:219], v143 offset:4096
	ds_read_b128 v[220:223], v143 offset:6144
	s_waitcnt lgkmcnt(3)
	v_mfma_f32_16x16x32_bf16 v[128:131], v[200:203], v[148:151], v[128:131]
	v_mfma_f32_16x16x32_bf16 v[124:127], v[204:207], v[148:151], v[124:127]
	v_mfma_f32_16x16x32_bf16 v[120:123], v[208:211], v[148:151], v[120:123]
	v_mfma_f32_16x16x32_bf16 v[116:119], v[212:215], v[148:151], v[116:119]
	s_waitcnt lgkmcnt(2)
	v_mfma_f32_16x16x32_bf16 v[112:115], v[200:203], v[152:155], v[112:115]
	v_mfma_f32_16x16x32_bf16 v[108:111], v[204:207], v[152:155], v[108:111]
	v_mfma_f32_16x16x32_bf16 v[104:107], v[208:211], v[152:155], v[104:107]
	v_mfma_f32_16x16x32_bf16 v[100:103], v[212:215], v[152:155], v[100:103]
	ds_read_b128 v[148:151], v143 offset:8192
	ds_read_b128 v[152:155], v143 offset:10240
	s_waitcnt lgkmcnt(3)
; __device__ __forceinline__ void gemm_core_big(const bf16_t* __restrict__ A, int lda, const bf16_t* __restrict__ Bt, int ldb,
;                                               int K, f32x4 (&acc)[8][4], char* smem) {
;     ...
; #pragma unroll
;     for (int ks = 0; ks < 2; ++ks) {
;       const int fo = ks ? fo1 : fo0;
;       bf16x8 bfr[4];
; #pragma unroll
;       for (int j = 0; j < 4; ++j) bfr[j] = *(const bf16x8*)(cB + j * 16 * LDS_STRIDE + fo);
; #pragma unroll
;       for (int i = 0; i < 8; ++i) {
;         const bf16x8 af = *(const bf16x8*)(cA + i * 16 * LDS_STRIDE + fo);
; #pragma unroll
;         for (int j = 0; j < 4; ++j)
;           acc[i][j] = __builtin_amdgcn_mfma_f32_16x16x32_bf16(bfr[j], af, acc[i][j], 0, 0, 0);
;       }
;     }
	v_mfma_f32_16x16x32_bf16 v[96:99], v[200:203], v[216:219], v[96:99]
	v_mfma_f32_16x16x32_bf16 v[92:95], v[204:207], v[216:219], v[92:95]
	v_mfma_f32_16x16x32_bf16 v[88:91], v[208:211], v[216:219], v[88:91]
	v_mfma_f32_16x16x32_bf16 v[84:87], v[212:215], v[216:219], v[84:87]
	s_waitcnt lgkmcnt(2)
	v_mfma_f32_16x16x32_bf16 v[80:83], v[200:203], v[220:223], v[80:83]
	v_mfma_f32_16x16x32_bf16 v[76:79], v[204:207], v[220:223], v[76:79]
	v_mfma_f32_16x16x32_bf16 v[72:75], v[208:211], v[220:223], v[72:75]
	v_mfma_f32_16x16x32_bf16 v[68:71], v[212:215], v[220:223], v[68:71]
	ds_read_b128 v[216:219], v143 offset:12288
	ds_read_b128 v[220:223], v143 offset:14336
	s_waitcnt lgkmcnt(3)
	v_mfma_f32_16x16x32_bf16 v[64:67], v[200:203], v[148:151], v[64:67]
	v_mfma_f32_16x16x32_bf16 v[60:63], v[204:207], v[148:151], v[60:63]
	v_mfma_f32_16x16x32_bf16 v[56:59], v[208:211], v[148:151], v[56:59]
	v_mfma_f32_16x16x32_bf16 v[52:55], v[212:215], v[148:151], v[52:55]
	s_waitcnt lgkmcnt(2)
	v_mfma_f32_16x16x32_bf16 v[48:51], v[200:203], v[152:155], v[48:51]
	v_mfma_f32_16x16x32_bf16 v[44:47], v[204:207], v[152:155], v[44:47]
	v_mfma_f32_16x16x32_bf16 v[40:43], v[208:211], v[152:155], v[40:43]
	v_mfma_f32_16x16x32_bf16 v[36:39], v[212:215], v[152:155], v[36:39]
	s_waitcnt lgkmcnt(1)
	v_mfma_f32_16x16x32_bf16 v[32:35], v[200:203], v[216:219], v[32:35]
	v_mfma_f32_16x16x32_bf16 v[24:27], v[204:207], v[216:219], v[24:27]
	v_mfma_f32_16x16x32_bf16 v[20:23], v[208:211], v[216:219], v[20:23]
	v_mfma_f32_16x16x32_bf16 v[16:19], v[212:215], v[216:219], v[16:19]
	s_waitcnt lgkmcnt(0)
	v_mfma_f32_16x16x32_bf16 v[12:15], v[200:203], v[220:223], v[12:15]
	v_mfma_f32_16x16x32_bf16 v[8:11], v[204:207], v[220:223], v[8:11]
	v_mfma_f32_16x16x32_bf16 v[4:7], v[208:211], v[220:223], v[4:7]
	v_mfma_f32_16x16x32_bf16 v[28:31], v[212:215], v[220:223], v[28:31]
	s_cbranch_scc1 .LBB0_711
; __device__ __forceinline__ unsigned pack2(float a, float b) { return (unsigned)f2bf(a) | ((unsigned)f2bf(b) << 16); }
; __device__ __forceinline__ void phase_gemm_in(const Params& p, char* smem) {
;     ...
;     bf16_t* dst; int ldd, ncol0;
;     if (nt < PRE_W / 128) { dst = PRE; ldd = PRE_W; ncol0 = nt * 128; }
;     else { dst = POST; ldd = POST_W; ncol0 = (nt - PRE_W / 128) * 128; }
; #pragma unroll
;     for (int i = 0; i < 8; ++i) {
;       const int m = mt * 256 + wm * 128 + i * 16 + (lane & 15);
; #pragma unroll
;       for (int j = 0; j < 4; ++j) {
;         const int n = ncol0 + wn * 64 + j * 16 + (lane >> 4) * 4;
;         uint2 o;
;         o.x = pack2(acc[i][j][0], acc[i][j][1]);
;         o.y = pack2(acc[i][j][2], acc[i][j][3]);
;         *(uint2*)(dst + (size_t)m * ldd + n) = o;
;       }
;     }
	s_setprio 0
	s_lshl_b32 s13, s14, 7
	s_add_i32 s15, s13, 0xffffef00
	s_cmp_lt_i32 s14, 34
	s_mov_b32 s14, 0x4100000
	s_cselect_b32 s18, s14, 0xcb20000
	s_movk_i32 s0, 0x1200
	s_cselect_b32 s15, s13, s15
	s_cselect_b32 s14, 0x1100, s0
	v_lshl_add_u32 v2, s12, 8, v138
	s_add_u32 s12, s10, s18
	v_or_b32_e32 v0, s15, v139
	s_addc_u32 s13, s11, 0
	v_ashrrev_i32_e32 v1, 31, v0
	v_lshlrev_b64 v[0:1], 1, v[0:1]
	v_bfe_u32 v134, v178, 4, 1
	v_mul_u32_u24_e32 v134, 24, v134
	v_add_u32_e32 v0, v0, v134
	v_mad_i64_i32 v[132:133], s[26:27], s14, v2, 0
	v_lshl_add_u64 v[132:133], v[132:133], 1, s[12:13]
	v_lshl_add_u64 v[132:133], v[132:133], 0, v[0:1]
	v_cvt_pk_bf16_f32 v144, v128, v129
	v_cvt_pk_bf16_f32 v146, v124, v125
	v_cvt_pk_bf16_f32 v145, v130, v131
	v_cvt_pk_bf16_f32 v147, v126, v127
	s_nop 1
	v_permlane16_swap_b32_e32 v144, v146
	v_permlane16_swap_b32_e32 v145, v147
	global_store_dwordx4 v[132:133], v[144:147], off
	v_cvt_pk_bf16_f32 v148, v120, v121
	v_cvt_pk_bf16_f32 v150, v116, v117
	v_cvt_pk_bf16_f32 v149, v122, v123
	v_cvt_pk_bf16_f32 v151, v118, v119
	s_nop 1
	v_permlane16_swap_b32_e32 v148, v150
	v_permlane16_swap_b32_e32 v149, v151
	global_store_dwordx4 v[132:133], v[148:151], off offset:64
	v_or_b32_e32 v162, 0x10, v2
	v_mad_i64_i32 v[160:161], s[26:27], s14, v162, 0
	v_lshl_add_u64 v[160:161], v[160:161], 1, s[12:13]
	v_lshl_add_u64 v[160:161], v[160:161], 0, v[0:1]
	v_cvt_pk_bf16_f32 v152, v112, v113
	v_cvt_pk_bf16_f32 v154, v108, v109
	v_cvt_pk_bf16_f32 v153, v114, v115
	v_cvt_pk_bf16_f32 v155, v110, v111
	s_nop 1
	v_permlane16_swap_b32_e32 v152, v154
	v_permlane16_swap_b32_e32 v153, v155
	global_store_dwordx4 v[160:161], v[152:155], off
	v_cvt_pk_bf16_f32 v156, v104, v105
	v_cvt_pk_bf16_f32 v158, v100, v101
	v_cvt_pk_bf16_f32 v157, v106, v107
	v_cvt_pk_bf16_f32 v159, v102, v103
	s_nop 1
	v_permlane16_swap_b32_e32 v156, v158
	v_permlane16_swap_b32_e32 v157, v159
	global_store_dwordx4 v[160:161], v[156:159], off offset:64
	v_or_b32_e32 v162, 0x20, v2
	v_mad_i64_i32 v[132:133], s[26:27], s14, v162, 0
	v_lshl_add_u64 v[132:133], v[132:133], 1, s[12:13]
	v_lshl_add_u64 v[132:133], v[132:133], 0, v[0:1]
	v_cvt_pk_bf16_f32 v144, v96, v97
	v_cvt_pk_bf16_f32 v146, v92, v93
	v_cvt_pk_bf16_f32 v145, v98, v99
	v_cvt_pk_bf16_f32 v147, v94, v95
	s_nop 1
	v_permlane16_swap_b32_e32 v144, v146
	v_permlane16_swap_b32_e32 v145, v147
	global_store_dwordx4 v[132:133], v[144:147], off
	v_cvt_pk_bf16_f32 v148, v88, v89
	v_cvt_pk_bf16_f32 v150, v84, v85
	v_cvt_pk_bf16_f32 v149, v90, v91
	v_cvt_pk_bf16_f32 v151, v86, v87
	s_nop 1
	v_permlane16_swap_b32_e32 v148, v150
	v_permlane16_swap_b32_e32 v149, v151
	global_store_dwordx4 v[132:133], v[148:151], off offset:64
	v_or_b32_e32 v162, 0x30, v2
	v_mad_i64_i32 v[160:161], s[26:27], s14, v162, 0
	v_lshl_add_u64 v[160:161], v[160:161], 1, s[12:13]
	v_lshl_add_u64 v[160:161], v[160:161], 0, v[0:1]
	v_cvt_pk_bf16_f32 v152, v80, v81
	v_cvt_pk_bf16_f32 v154, v76, v77
	v_cvt_pk_bf16_f32 v153, v82, v83
	v_cvt_pk_bf16_f32 v155, v78, v79
	s_nop 1
	v_permlane16_swap_b32_e32 v152, v154
	v_permlane16_swap_b32_e32 v153, v155
	global_store_dwordx4 v[160:161], v[152:155], off
	v_cvt_pk_bf16_f32 v156, v72, v73
	v_cvt_pk_bf16_f32 v158, v68, v69
	v_cvt_pk_bf16_f32 v157, v74, v75
	v_cvt_pk_bf16_f32 v159, v70, v71
	s_nop 1
	v_permlane16_swap_b32_e32 v156, v158
	v_permlane16_swap_b32_e32 v157, v159
	global_store_dwordx4 v[160:161], v[156:159], off offset:64
	v_or_b32_e32 v162, 0x40, v2
	v_mad_i64_i32 v[132:133], s[26:27], s14, v162, 0
	v_lshl_add_u64 v[132:133], v[132:133], 1, s[12:13]
	v_lshl_add_u64 v[132:133], v[132:133], 0, v[0:1]
	v_cvt_pk_bf16_f32 v144, v64, v65
	v_cvt_pk_bf16_f32 v146, v60, v61
	v_cvt_pk_bf16_f32 v145, v66, v67
	v_cvt_pk_bf16_f32 v147, v62, v63
	s_nop 1
	v_permlane16_swap_b32_e32 v144, v146
	v_permlane16_swap_b32_e32 v145, v147
	global_store_dwordx4 v[132:133], v[144:147], off
	v_cvt_pk_bf16_f32 v148, v56, v57
	v_cvt_pk_bf16_f32 v150, v52, v53
	v_cvt_pk_bf16_f32 v149, v58, v59
	v_cvt_pk_bf16_f32 v151, v54, v55
	s_nop 1
	v_permlane16_swap_b32_e32 v148, v150
	v_permlane16_swap_b32_e32 v149, v151
	global_store_dwordx4 v[132:133], v[148:151], off offset:64
	v_or_b32_e32 v162, 0x50, v2
	v_mad_i64_i32 v[160:161], s[26:27], s14, v162, 0
	v_lshl_add_u64 v[160:161], v[160:161], 1, s[12:13]
	v_lshl_add_u64 v[160:161], v[160:161], 0, v[0:1]
	v_cvt_pk_bf16_f32 v152, v48, v49
	v_cvt_pk_bf16_f32 v154, v44, v45
	v_cvt_pk_bf16_f32 v153, v50, v51
	v_cvt_pk_bf16_f32 v155, v46, v47
	s_nop 1
	v_permlane16_swap_b32_e32 v152, v154
	v_permlane16_swap_b32_e32 v153, v155
	global_store_dwordx4 v[160:161], v[152:155], off
	v_cvt_pk_bf16_f32 v156, v40, v41
	v_cvt_pk_bf16_f32 v158, v36, v37
	v_cvt_pk_bf16_f32 v157, v42, v43
	v_cvt_pk_bf16_f32 v159, v38, v39
	s_nop 1
	v_permlane16_swap_b32_e32 v156, v158
	v_permlane16_swap_b32_e32 v157, v159
	global_store_dwordx4 v[160:161], v[156:159], off offset:64
	v_or_b32_e32 v162, 0x60, v2
	v_mad_i64_i32 v[132:133], s[26:27], s14, v162, 0
	v_lshl_add_u64 v[132:133], v[132:133], 1, s[12:13]
	v_lshl_add_u64 v[132:133], v[132:133], 0, v[0:1]
	v_cvt_pk_bf16_f32 v144, v32, v33
	v_cvt_pk_bf16_f32 v146, v24, v25
	v_cvt_pk_bf16_f32 v145, v34, v35
	v_cvt_pk_bf16_f32 v147, v26, v27
	s_nop 1
	v_permlane16_swap_b32_e32 v144, v146
	v_permlane16_swap_b32_e32 v145, v147
	global_store_dwordx4 v[132:133], v[144:147], off
	v_cvt_pk_bf16_f32 v148, v20, v21
	v_cvt_pk_bf16_f32 v150, v16, v17
	v_cvt_pk_bf16_f32 v149, v22, v23
	v_cvt_pk_bf16_f32 v151, v18, v19
	s_nop 1
	v_permlane16_swap_b32_e32 v148, v150
	v_permlane16_swap_b32_e32 v149, v151
	global_store_dwordx4 v[132:133], v[148:151], off offset:64
	v_or_b32_e32 v162, 0x70, v2
	v_mad_i64_i32 v[160:161], s[26:27], s14, v162, 0
	v_lshl_add_u64 v[160:161], v[160:161], 1, s[12:13]
	v_lshl_add_u64 v[160:161], v[160:161], 0, v[0:1]
	v_cvt_pk_bf16_f32 v152, v12, v13
	v_cvt_pk_bf16_f32 v154, v8, v9
	v_cvt_pk_bf16_f32 v153, v14, v15
	v_cvt_pk_bf16_f32 v155, v10, v11
	s_nop 1
	v_permlane16_swap_b32_e32 v152, v154
	v_permlane16_swap_b32_e32 v153, v155
	global_store_dwordx4 v[160:161], v[152:155], off
	v_cvt_pk_bf16_f32 v156, v4, v5
	v_cvt_pk_bf16_f32 v158, v28, v29
	v_cvt_pk_bf16_f32 v157, v6, v7
	v_cvt_pk_bf16_f32 v159, v30, v31
	s_nop 1
	v_permlane16_swap_b32_e32 v156, v158
	v_permlane16_swap_b32_e32 v157, v159
	global_store_dwordx4 v[160:161], v[156:159], off offset:64
	s_add_i32 s23, s23, 1
	s_cmp_eq_u32 s23, s17
	s_cselect_b64 s[12:13], -1, 0
	s_mov_b32 s31, 0x18000
	s_branch .LBB0_708
